# grid barriers 12 and 13 become XCC-local when a run-time census shows each of the 8 blockIdx%8 groups sits on exactly one XCC (decision identical on every leader); otherwise unchanged
# speedup vs baseline: 1.0006x; 1.0006x over previous
.LBB0_1430:
	s_mov_b64 s[8:9], exec
	s_lshl_b32 s3, s3, 8
	v_mbcnt_lo_u32_b32 v2, s8, 0
	s_add_u32 s6, s4, s3
	v_mbcnt_hi_u32_b32 v2, s9, v2
	s_addc_u32 s7, s5, 0
	v_cmp_eq_u32_e32 vcc, 0, v2
	s_and_saveexec_b64 s[10:11], vcc
	s_cbranch_execz .LBB0_1432
	s_bcnt1_i32_b64 s3, s[8:9]
	v_mov_b32_e32 v4, 0x1000
	v_mov_b32_e32 v5, s3
	v_mov_b32_e32 v252, 0
	global_load_dwordx4 v[240:243], v252, s[34:35] offset:3584 sc1
	global_load_dwordx4 v[244:247], v252, s[34:35] offset:3600 sc1
	global_atomic_add v4, v4, v5, s[6:7] offset:1024 sc0

.LBB0_1446:
	s_andn2_saveexec_b64 s[8:9], s[8:9]
	s_cbranch_execz .LBB0_1466
	s_mov_b64 s[8:9], exec
	s_mov_b32 s98, 0
	v_readfirstlane_b32 s99, v240
	s_bcnt1_i32_b32 s99, s99
	s_xor_b32 s99, s99, 1
	s_or_b32 s98, s98, s99
	v_readfirstlane_b32 s99, v241
	s_bcnt1_i32_b32 s99, s99
	s_xor_b32 s99, s99, 1
	s_or_b32 s98, s98, s99
	v_readfirstlane_b32 s99, v242
	s_bcnt1_i32_b32 s99, s99
	s_xor_b32 s99, s99, 1
	s_or_b32 s98, s98, s99
	v_readfirstlane_b32 s99, v243
	s_bcnt1_i32_b32 s99, s99
	s_xor_b32 s99, s99, 1
	s_or_b32 s98, s98, s99
	v_readfirstlane_b32 s99, v244
	s_bcnt1_i32_b32 s99, s99
	s_xor_b32 s99, s99, 1
	s_or_b32 s98, s98, s99
	v_readfirstlane_b32 s99, v245
	s_bcnt1_i32_b32 s99, s99
	s_xor_b32 s99, s99, 1
	s_or_b32 s98, s98, s99
	v_readfirstlane_b32 s99, v246
	s_bcnt1_i32_b32 s99, s99
	s_xor_b32 s99, s99, 1
	s_or_b32 s98, s98, s99
	v_readfirstlane_b32 s99, v247
	s_bcnt1_i32_b32 s99, s99
	s_xor_b32 s99, s99, 1
	s_or_b32 s98, s98, s99
	s_cmpk_lg_i32 s94, 0x100
	s_cbranch_scc1 xl_glob_b12
	s_cmp_eq_u32 s98, 0
	s_cbranch_scc1 xl_tail_b12

.LBB0_1518:
	s_andn2_saveexec_b64 s[8:9], s[8:9]
	s_cbranch_execz .LBB0_1538
	s_mov_b64 s[8:9], exec
	s_mov_b32 s98, 0
	v_readfirstlane_b32 s99, v240
	s_bcnt1_i32_b32 s99, s99
	s_xor_b32 s99, s99, 1
	s_or_b32 s98, s98, s99
	v_readfirstlane_b32 s99, v241
	s_bcnt1_i32_b32 s99, s99
	s_xor_b32 s99, s99, 1
	s_or_b32 s98, s98, s99
	v_readfirstlane_b32 s99, v242
	s_bcnt1_i32_b32 s99, s99
	s_xor_b32 s99, s99, 1
	s_or_b32 s98, s98, s99
	v_readfirstlane_b32 s99, v243
	s_bcnt1_i32_b32 s99, s99
	s_xor_b32 s99, s99, 1
	s_or_b32 s98, s98, s99
	v_readfirstlane_b32 s99, v244
	s_bcnt1_i32_b32 s99, s99
	s_xor_b32 s99, s99, 1
	s_or_b32 s98, s98, s99
	v_readfirstlane_b32 s99, v245
	s_bcnt1_i32_b32 s99, s99
	s_xor_b32 s99, s99, 1
	s_or_b32 s98, s98, s99
	v_readfirstlane_b32 s99, v246
	s_bcnt1_i32_b32 s99, s99
	s_xor_b32 s99, s99, 1
	s_or_b32 s98, s98, s99
	v_readfirstlane_b32 s99, v247
	s_bcnt1_i32_b32 s99, s99
	s_xor_b32 s99, s99, 1
	s_or_b32 s98, s98, s99
	s_cmpk_lg_i32 s94, 0x100
	s_cbranch_scc1 xl_glob_b13
	s_cmp_eq_u32 s98, 0
	s_cbranch_scc1 xl_tail_b13
